# v105 + attention prompt softmax: v_fmamk_f32 instead of v_sub+v_mul before each exp (41 fewer VALU per q-tile)
# speedup vs baseline: 1.0076x; 1.0039x over previous
.Lqk_done:
	ds_bpermute_b32 v13, v55, v10
	s_waitcnt lgkmcnt(0)
	v_max_f32_e32 v13, v13, v13
	v_max_f32_e32 v10, v10, v13
	ds_bpermute_b32 v13, v56, v10
	s_waitcnt vmcnt(0) lgkmcnt(0)
	v_max3_f32 v10, v10, v13, v37
	v_mul_f32_e32 v156, 0xbfb8aa3b, v10
	v_fmamk_f32 v14, v62, 0x3fb8aa3b, v156
	v_exp_f32_e32 v94, v14
	v_fmamk_f32 v14, v61, 0x3fb8aa3b, v156
	v_exp_f32_e32 v95, v14
	v_fmamk_f32 v14, v60, 0x3fb8aa3b, v156
	v_exp_f32_e32 v96, v14
	v_fmamk_f32 v14, v66, 0x3fb8aa3b, v156
	v_exp_f32_e32 v97, v14
	v_fmamk_f32 v14, v65, 0x3fb8aa3b, v156
	v_exp_f32_e32 v102, v14
	v_fmamk_f32 v14, v64, 0x3fb8aa3b, v156
	v_exp_f32_e32 v103, v14
	v_fmamk_f32 v14, v63, 0x3fb8aa3b, v156
	v_exp_f32_e32 v104, v14
	v_fmamk_f32 v14, v71, 0x3fb8aa3b, v156
	v_exp_f32_e32 v105, v14
	v_fmamk_f32 v14, v70, 0x3fb8aa3b, v156
	v_exp_f32_e32 v106, v14
	v_fmamk_f32 v14, v69, 0x3fb8aa3b, v156
	v_exp_f32_e32 v107, v14
	v_fmamk_f32 v14, v68, 0x3fb8aa3b, v156
	v_exp_f32_e32 v108, v14
	v_fmamk_f32 v14, v75, 0x3fb8aa3b, v156
	v_exp_f32_e32 v109, v14
	v_fmamk_f32 v14, v74, 0x3fb8aa3b, v156
	v_exp_f32_e32 v110, v14
	v_fmamk_f32 v14, v73, 0x3fb8aa3b, v156
	v_exp_f32_e32 v111, v14
	v_fmamk_f32 v14, v72, 0x3fb8aa3b, v156
	v_fmamk_f32 v13, v59, 0x3fb8aa3b, v156
	v_exp_f32_e32 v112, v14
	v_fmamk_f32 v14, v79, 0x3fb8aa3b, v156
	v_exp_f32_e32 v93, v13
	v_exp_f32_e32 v66, v14
	v_fmamk_f32 v14, v78, 0x3fb8aa3b, v156
	v_exp_f32_e32 v69, v14
	v_fmamk_f32 v14, v77, 0x3fb8aa3b, v156
	v_add_f32_e32 v13, 0, v93
	v_add_f32_e32 v13, v94, v13
	v_exp_f32_e32 v71, v14
	v_fmamk_f32 v14, v76, 0x3fb8aa3b, v156
	v_add_f32_e32 v13, v95, v13
	v_add_f32_e32 v13, v96, v13
	v_exp_f32_e32 v72, v14
	v_fmamk_f32 v14, v83, 0x3fb8aa3b, v156
	v_add_f32_e32 v13, v97, v13
	v_add_f32_e32 v13, v102, v13
	v_exp_f32_e32 v73, v14
	v_fmamk_f32 v14, v82, 0x3fb8aa3b, v156
	v_add_f32_e32 v13, v103, v13
	v_add_f32_e32 v13, v104, v13
	v_exp_f32_e32 v113, v14
	v_fmamk_f32 v14, v81, 0x3fb8aa3b, v156
	v_add_f32_e32 v13, v105, v13
	v_add_f32_e32 v13, v106, v13
	v_exp_f32_e32 v114, v14
	v_fmamk_f32 v14, v80, 0x3fb8aa3b, v156
	v_add_f32_e32 v13, v107, v13
	v_add_f32_e32 v13, v108, v13
	v_exp_f32_e32 v115, v14
	v_fmamk_f32 v14, v87, 0x3fb8aa3b, v156
	v_add_f32_e32 v13, v109, v13
	v_add_f32_e32 v13, v110, v13
	v_exp_f32_e32 v61, v14
	v_fmamk_f32 v14, v86, 0x3fb8aa3b, v156
	v_add_f32_e32 v13, v111, v13
	v_add_f32_e32 v13, v112, v13
	v_exp_f32_e32 v62, v14
	v_fmamk_f32 v14, v85, 0x3fb8aa3b, v156
	v_add_f32_e32 v13, v66, v13
	v_add_f32_e32 v13, v69, v13
	v_exp_f32_e32 v63, v14
	v_fmamk_f32 v14, v84, 0x3fb8aa3b, v156
	v_add_f32_e32 v13, v71, v13
	v_add_f32_e32 v13, v72, v13
	v_exp_f32_e32 v64, v14
	v_fmamk_f32 v14, v100, 0x3fb8aa3b, v156
	v_add_f32_e32 v13, v73, v13
	v_add_f32_e32 v13, v113, v13
	v_exp_f32_e32 v65, v14
	v_fmamk_f32 v14, v90, 0x3fb8aa3b, v156
	v_add_f32_e32 v13, v114, v13
	v_add_f32_e32 v13, v115, v13
	v_exp_f32_e32 v67, v14
	v_fmamk_f32 v14, v89, 0x3fb8aa3b, v156
	v_add_f32_e32 v13, v61, v13
	v_add_f32_e32 v13, v62, v13
	v_exp_f32_e32 v68, v14
	v_fmamk_f32 v14, v88, 0x3fb8aa3b, v156
	v_add_f32_e32 v13, v63, v13
	v_add_f32_e32 v13, v64, v13
	v_exp_f32_e32 v70, v14
	v_add_f32_e32 v13, v65, v13
	v_add_f32_e32 v13, v67, v13
	v_add_f32_e32 v13, v68, v13
	v_add_f32_e32 v14, v70, v13
	v_fmamk_f32 v13, v98, 0x3fb8aa3b, v156
	v_exp_f32_e32 v13, v13
	v_fmamk_f32 v17, v17, 0x3fb8aa3b, v156
	v_exp_f32_e32 v17, v17
	v_add_f32_e32 v15, v13, v14
	v_fmamk_f32 v14, v99, 0x3fb8aa3b, v156
	v_exp_f32_e32 v14, v14
	v_fmamk_f32 v11, v11, 0x3fb8aa3b, v156
	v_lshl_add_u32 v90, s37, 5, v49
	v_add_f32_e32 v16, v14, v15
	v_fmamk_f32 v15, v101, 0x3fb8aa3b, v156
	v_exp_f32_e32 v15, v15
	v_add_u32_e32 v78, 0x9000, v90
	ds_read2_b64 v[78:81], v78 offset1:4
	v_fmamk_f32 v12, v12, 0x3fb8aa3b, v156
	v_add_f32_e32 v58, v15, v16
	v_fmamk_f32 v16, v91, 0x3fb8aa3b, v156
	v_exp_f32_e32 v16, v16
	v_add_u32_e32 v82, 0xb000, v90
	v_add_u32_e32 v86, 0xd000, v90
	v_add_f32_e32 v58, v16, v58
	v_add_f32_e32 v59, v17, v58
	v_exp_f32_e32 v58, v11
	v_add_u32_e32 v90, 0xf000, v90
	v_lshl_add_u32 v98, s67, 5, v49
	v_cvt_pk_bf16_f32 v74, v93, v94
	v_add_f32_e32 v11, v58, v59
	v_exp_f32_e32 v59, v12
	v_fmamk_f32 v12, v92, 0x3fb8aa3b, v156
	ds_read2_b64 v[82:85], v82 offset0:32 offset1:36
	ds_read2_b64 v[86:89], v86 offset0:64 offset1:68
	ds_read2_b64 v[90:93], v90 offset0:96 offset1:100
	v_add_u32_e32 v94, 0x9000, v98
	v_cvt_pk_bf16_f32 v75, v95, v96
	v_cvt_pk_bf16_f32 v76, v97, v102
	ds_read2_b64 v[94:97], v94 offset1:4
	v_cvt_pk_bf16_f32 v77, v103, v104
	v_cvt_pk_bf16_f32 v62, v61, v62
	v_lshl_add_u32 v61, s77, 5, v49
	s_waitcnt lgkmcnt(4)
	v_mfma_f32_16x16x32_bf16 v[78:81], v[78:81], v[74:77], 0
	v_cvt_pk_bf16_f32 v63, v63, v64
	v_cvt_pk_bf16_f32 v64, v65, v67
	v_cvt_pk_bf16_f32 v65, v68, v70
	s_waitcnt lgkmcnt(3)
	v_mfma_f32_16x16x32_bf16 v[82:85], v[82:85], v[74:77], 0
	v_add_u32_e32 v70, 0xb000, v61
	v_exp_f32_e32 v60, v12
	s_waitcnt lgkmcnt(2)
	v_mfma_f32_16x16x32_bf16 v[86:89], v[86:89], v[74:77], 0
	v_cvt_pk_bf16_f32 v14, v13, v14
	v_lshl_add_u32 v13, s34, 5, v49
	v_add_f32_e32 v11, v59, v11
	s_waitcnt lgkmcnt(1)
	v_mfma_f32_16x16x32_bf16 v[74:77], v[90:93], v[74:77], 0
	v_cvt_pk_bf16_f32 v90, v105, v106
	v_cvt_pk_bf16_f32 v91, v107, v108
	v_cvt_pk_bf16_f32 v92, v109, v110
	v_cvt_pk_bf16_f32 v93, v111, v112
	v_cvt_pk_bf16_f32 v15, v15, v16
	v_cvt_pk_bf16_f32 v16, v17, v58
	s_waitcnt lgkmcnt(0)
	v_mfma_f32_16x16x32_bf16 v[78:81], v[94:97], v[90:93], v[78:81]
	v_add_u32_e32 v94, 0xb000, v98
	ds_read2_b64 v[94:97], v94 offset0:32 offset1:36
	v_add_u32_e32 v58, 0x9000, v13
	s_waitcnt lgkmcnt(0)
	v_mfma_f32_16x16x32_bf16 v[82:85], v[94:97], v[90:93], v[82:85]
	v_add_u32_e32 v94, 0xd000, v98
	ds_read2_b64 v[94:97], v94 offset0:64 offset1:68
	v_add_f32_e32 v11, v60, v11
	s_waitcnt lgkmcnt(0)
	v_mfma_f32_16x16x32_bf16 v[86:89], v[94:97], v[90:93], v[86:89]
	v_add_u32_e32 v94, 0xf000, v98
	ds_read2_b64 v[94:97], v94 offset0:96 offset1:100
	v_cvt_pk_bf16_f32 v17, v59, v60
	s_waitcnt lgkmcnt(0)
	v_mfma_f32_16x16x32_bf16 v[74:77], v[94:97], v[90:93], v[74:77]
	v_cvt_pk_bf16_f32 v90, v66, v69
	v_lshl_add_u32 v66, s76, 5, v49
	v_add_u32_e32 v69, 0x9000, v66
	ds_read2_b64 v[94:97], v69 offset1:4
	v_cvt_pk_bf16_f32 v91, v71, v72
	v_cvt_pk_bf16_f32 v92, v73, v113
	v_cvt_pk_bf16_f32 v93, v114, v115
	v_add_u32_e32 v69, 0xb000, v66
	ds_bpermute_b32 v12, v55, v11
	s_waitcnt lgkmcnt(1)
	v_mfma_f32_16x16x32_bf16 v[78:81], v[94:97], v[90:93], v[78:81]
	ds_read2_b64 v[94:97], v69 offset0:32 offset1:36
	v_add_u32_e32 v69, 0xd000, v66
	v_add_u32_e32 v66, 0xf000, v66
	s_waitcnt lgkmcnt(0)
	v_mfma_f32_16x16x32_bf16 v[82:85], v[94:97], v[90:93], v[82:85]
	ds_read2_b64 v[94:97], v69 offset0:64 offset1:68
	v_add_f32_e32 v11, v11, v12
	ds_bpermute_b32 v12, v56, v11
	s_waitcnt lgkmcnt(1)
	v_mfma_f32_16x16x32_bf16 v[86:89], v[94:97], v[90:93], v[86:89]
	ds_read2_b64 v[94:97], v66 offset0:96 offset1:100
	v_add_u32_e32 v66, 0x9000, v61
	ds_read2_b64 v[66:69], v66 offset1:4
	s_waitcnt lgkmcnt(1)
	v_mfma_f32_16x16x32_bf16 v[72:75], v[94:97], v[90:93], v[74:77]
	v_fmamk_f32 v10, v37, 0x3fb8aa3b, v156
	v_exp_f32_e32 v10, v10
	s_waitcnt lgkmcnt(0)
	v_mfma_f32_16x16x32_bf16 v[66:69], v[66:69], v[62:65], v[78:81]
	v_add_f32_e32 v11, v11, v12
	v_add_f32_e32 v10, v10, v11
	s_nop 0
	ds_read2_b64 v[76:79], v70 offset0:32 offset1:36
	v_add_u32_e32 v70, 0xd000, v61
	s_waitcnt lgkmcnt(0)
	v_mfma_f32_16x16x32_bf16 v[76:79], v[76:79], v[62:65], v[82:85]
	s_nop 2
	ds_read2_b64 v[80:83], v70 offset0:64 offset1:68
	v_add_u32_e32 v61, 0xf000, v61
	v_add_u32_e32 v70, 0xd000, v13
	s_waitcnt lgkmcnt(0)
	v_mfma_f32_16x16x32_bf16 v[80:83], v[80:83], v[62:65], v[86:89]
	s_nop 2
	ds_read2_b64 v[84:87], v61 offset0:96 offset1:100
	ds_read2_b64 v[58:61], v58 offset1:4
	v_div_scale_f32 v11, s[34:35], v10, v10, 1.0
	s_waitcnt lgkmcnt(0)
	v_mfma_f32_16x16x32_bf16 v[58:61], v[58:61], v[14:17], v[66:69]
	s_nop 2
	v_add_u32_e32 v66, 0xb000, v13
	ds_read2_b64 v[66:69], v66 offset0:32 offset1:36
	v_add_u32_e32 v13, 0xf000, v13
	v_mfma_f32_16x16x32_bf16 v[62:65], v[84:87], v[62:65], v[72:75]
	v_rcp_f32_e32 v12, v11
	s_mov_b32 s34, s36
	s_waitcnt lgkmcnt(0)
	v_mfma_f32_16x16x32_bf16 v[66:69], v[66:69], v[14:17], v[76:79]
	ds_read2_b64 v[70:73], v70 offset0:64 offset1:68
	s_nop 1
	ds_read2_b64 v[74:77], v13 offset0:96 offset1:100
	v_fma_f32 v13, -v11, v12, 1.0
	v_fmac_f32_e32 v12, v13, v12
	v_div_scale_f32 v13, vcc, 1.0, v10, 1.0
	s_waitcnt lgkmcnt(1)
	v_mfma_f32_16x16x32_bf16 v[70:73], v[70:73], v[14:17], v[80:83]
	s_waitcnt lgkmcnt(0)
	v_mfma_f32_16x16x32_bf16 v[14:17], v[74:77], v[14:17], v[62:65]
	s_nop 2
	v_mul_f32_e32 v62, v13, v12
	v_fma_f32 v63, -v11, v62, v13
	v_fmac_f32_e32 v62, v63, v12
	v_fma_f32 v11, -v11, v62, v13
	v_div_fmas_f32 v11, v11, v12, v62
	v_div_fixup_f32 v10, v11, v10, 1.0
	v_pk_mul_f32 v[12:13], v[60:61], v[10:11] op_sel_hi:[1,0]
	v_pk_mul_f32 v[58:59], v[58:59], v[10:11] op_sel_hi:[1,0]
	v_pk_mul_f32 v[16:17], v[10:11], v[16:17] op_sel_hi:[0,1]
	v_cvt_pk_bf16_f32 v58, v58, v59
	v_cvt_pk_bf16_f32 v59, v12, v13
	v_lshl_add_u64 v[12:13], v[38:39], 0, v[40:41]
	global_store_dwordx2 v[12:13], v[58:59], off
	v_pk_mul_f32 v[40:41], v[10:11], v[68:69] op_sel_hi:[0,1]
	v_pk_mul_f32 v[58:59], v[10:11], v[66:67] op_sel_hi:[0,1]
	v_cvt_pk_bf16_f32 v58, v58, v59
	v_cvt_pk_bf16_f32 v59, v40, v41
	global_store_dwordx2 v[12:13], v[58:59], off offset:32
	v_pk_mul_f32 v[40:41], v[10:11], v[72:73] op_sel_hi:[0,1]
	v_pk_mul_f32 v[58:59], v[10:11], v[70:71] op_sel_hi:[0,1]
	v_pk_mul_f32 v[10:11], v[10:11], v[14:15] op_sel_hi:[0,1]
	v_cvt_pk_bf16_f32 v58, v58, v59
	v_cvt_pk_bf16_f32 v59, v40, v41
	v_cvt_pk_bf16_f32 v10, v10, v11
	v_cvt_pk_bf16_f32 v11, v16, v17
	global_store_dwordx2 v[12:13], v[58:59], off offset:64
	global_store_dwordx2 v[12:13], v[10:11], off offset:96
	v_mov_b64_e32 v[16:17], v[8:9]
	v_mov_b64_e32 v[12:13], v[4:5]
	v_mov_b64_e32 v[14:15], v[6:7]
	v_mov_b64_e32 v[10:11], v[2:3]
	s_cbranch_scc1 .LBB0_1112
